# retention final-state GEMM: all K-tile loads issued up front (counted waits)
# baseline (speedup 1.0000x reference)
.LBB0_681:
	s_ashr_i32 s29, s28, 31
	v_mov_b32_e32 v7, v0
	s_lshl_b64 s[30:31], s[28:29], 16
	s_add_u32 s40, s2, s30
	v_ashrrev_i32_e32 v4, 3, v7
	v_ashrrev_i32_e32 v5, 31, v4
	s_addc_u32 s41, s3, s31
	v_lshlrev_b64 v[8:9], 9, v[4:5]
	v_lshlrev_b32_e32 v2, 4, v7
	s_add_u32 s30, s33, s30
	v_lshl_add_u64 v[8:9], s[40:41], 0, v[8:9]
	v_and_b32_e32 v2, 0x70, v2
	s_addc_u32 s31, s34, s31
	v_lshl_add_u64 v[92:93], v[8:9], 0, v[2:3]
	v_lshlrev_b64 v[8:9], 7, v[4:5]
	v_lshl_add_u64 v[8:9], s[30:31], 0, v[8:9]
	v_lshl_add_u64 v[94:95], v[8:9], 0, v[2:3]
	v_add_co_u32_e32 v8, vcc, s35, v92
	v_ashrrev_i32_e32 v5, 2, v7
	s_nop 0
	v_addc_co_u32_e32 v9, vcc, 0, v93, vcc
	global_load_dwordx4 v[8:11], v[8:9], off
	s_nop 0
	global_load_dwordx4 v[12:15], v[92:93], off
	global_load_dwordx4 v[16:19], v[94:95], off
	v_add_co_u32_e32 v20, vcc, s36, v94
	v_bfe_u32 v98, v7, 6, 2
	s_nop 0
	v_addc_co_u32_e32 v21, vcc, 0, v95, vcc
	global_load_dwordx4 v[20:23], v[20:21], off
	v_lshl_add_u64 v[200:201], v[92:93], 0, s[4:5]
	global_load_dwordx4 v[104:107], v[200:201], off
	v_lshl_add_u64 v[200:201], v[92:93], 0, s[8:9]
	global_load_dwordx4 v[108:111], v[200:201], off
	v_lshl_add_u64 v[200:201], v[94:95], 0, s[6:7]
	global_load_dwordx4 v[112:115], v[200:201], off
	v_lshl_add_u64 v[200:201], v[94:95], 0, s[10:11]
	global_load_dwordx4 v[116:119], v[200:201], off
	v_lshl_add_u64 v[200:201], v[92:93], 0, s[12:13]
	global_load_dwordx4 v[168:171], v[200:201], off
	v_lshl_add_u64 v[200:201], v[92:93], 0, s[16:17]
	global_load_dwordx4 v[172:175], v[200:201], off
	v_lshl_add_u64 v[200:201], v[94:95], 0, s[14:15]
	global_load_dwordx4 v[176:179], v[200:201], off
	v_lshl_add_u64 v[200:201], v[94:95], 0, s[18:19]
	global_load_dwordx4 v[180:183], v[200:201], off
	v_lshl_add_u64 v[200:201], v[92:93], 0, s[20:21]
	global_load_dwordx4 v[184:187], v[200:201], off
	v_lshl_add_u64 v[200:201], v[92:93], 0, s[24:25]
	global_load_dwordx4 v[188:191], v[200:201], off
	v_lshl_add_u64 v[200:201], v[94:95], 0, s[22:23]
	global_load_dwordx4 v[192:195], v[200:201], off
	v_lshl_add_u64 v[200:201], v[94:95], 0, s[26:27]
	global_load_dwordx4 v[196:199], v[200:201], off
	v_and_b32_e32 v99, 15, v7
	v_bfe_u32 v100, v7, 4, 2
	v_mul_lo_u32 v4, v4, s37
	v_and_b32_e32 v7, 0xffffffc0, v5
	s_waitcnt vmcnt(20)
	v_lshl_or_b32 v24, v98, 5, v99
	v_add3_u32 v2, 0, v4, v2
	v_or_b32_e32 v4, v7, v99
	v_lshlrev_b32_e32 v5, 4, v100
	v_mul_u32_u24_e32 v24, 0xa0, v24
	v_mul_lo_u32 v4, v4, s37
	v_add3_u32 v102, 0, v24, v5
	v_add3_u32 v103, 0, v4, v5
	v_lshl_add_u64 v[4:5], v[92:93], 0, s[4:5]
	v_lshl_add_u64 v[24:25], v[92:93], 0, s[8:9]
	v_lshl_add_u64 v[26:27], v[94:95], 0, s[6:7]
	v_add_u32_e32 v101, 0xa000, v2
	s_waitcnt vmcnt(14)
	ds_write_b128 v2, v[12:15]
	ds_write_b128 v2, v[8:11] offset:10240
	s_waitcnt vmcnt(13)
	ds_write_b128 v2, v[16:19] offset:40960
	s_waitcnt vmcnt(12)
	ds_write_b128 v2, v[20:23] offset:51200
	s_waitcnt lgkmcnt(0)
	s_barrier
	v_lshl_add_u64 v[4:5], v[94:95], 0, s[10:11]
	ds_read_b128 v[24:27], v103
	ds_read_b128 v[28:31], v102 offset:40960
	ds_read_b128 v[32:35], v103 offset:64
	ds_read_b128 v[36:39], v102 offset:41024
	ds_read_b128 v[44:47], v102 offset:43520
	ds_read_b128 v[48:51], v102 offset:43584
	ds_read_b128 v[52:55], v103 offset:2560
	ds_read_b128 v[56:59], v103 offset:2624
	ds_read_b128 v[64:67], v103 offset:5120
	ds_read_b128 v[68:71], v103 offset:5184
	ds_read_b128 v[76:79], v103 offset:7680
	ds_read_b128 v[80:83], v103 offset:7744
	s_waitcnt lgkmcnt(10)
	v_mfma_f32_16x16x32_bf16 v[40:43], v[24:27], v[28:31], 0
	s_waitcnt lgkmcnt(7)
	v_mfma_f32_16x16x32_bf16 v[24:27], v[24:27], v[44:47], 0
	s_waitcnt lgkmcnt(5)
	v_mfma_f32_16x16x32_bf16 v[60:63], v[52:55], v[28:31], 0
	v_mfma_f32_16x16x32_bf16 v[52:55], v[52:55], v[44:47], 0
	s_waitcnt lgkmcnt(3)
	v_mfma_f32_16x16x32_bf16 v[72:75], v[64:67], v[28:31], 0
	v_mfma_f32_16x16x32_bf16 v[64:67], v[64:67], v[44:47], 0
	s_waitcnt lgkmcnt(1)
	v_mfma_f32_16x16x32_bf16 v[28:31], v[76:79], v[28:31], 0
	v_mfma_f32_16x16x32_bf16 v[44:47], v[76:79], v[44:47], 0
	v_mfma_f32_16x16x32_bf16 v[40:43], v[32:35], v[36:39], v[40:43]
	v_mfma_f32_16x16x32_bf16 v[24:27], v[32:35], v[48:51], v[24:27]
	v_mfma_f32_16x16x32_bf16 v[32:35], v[56:59], v[36:39], v[60:63]
	v_mfma_f32_16x16x32_bf16 v[52:55], v[56:59], v[48:51], v[52:55]
	v_mfma_f32_16x16x32_bf16 v[56:59], v[68:71], v[36:39], v[72:75]
	v_mfma_f32_16x16x32_bf16 v[60:63], v[68:71], v[48:51], v[64:67]
	s_waitcnt lgkmcnt(0)
	v_mfma_f32_16x16x32_bf16 v[28:31], v[80:83], v[36:39], v[28:31]
	v_mfma_f32_16x16x32_bf16 v[36:39], v[80:83], v[48:51], v[44:47]
	s_waitcnt vmcnt(8)
	v_lshl_add_u64 v[4:5], v[92:93], 0, s[12:13]
	ds_write_b128 v2, v[104:107] offset:20480
	ds_write_b128 v2, v[108:111] offset:30720
	ds_write_b128 v2, v[112:115] offset:61440
	ds_write_b128 v101, v[116:119] offset:30720
	s_waitcnt lgkmcnt(0)
	s_barrier
	v_lshl_add_u64 v[16:17], v[94:95], 0, s[14:15]
	v_lshl_add_u64 v[4:5], v[92:93], 0, s[16:17]
	v_lshl_add_u64 v[4:5], v[94:95], 0, s[18:19]
	ds_read_b128 v[44:47], v103 offset:20480
	ds_read_b128 v[48:51], v102 offset:61440
	ds_read_b128 v[64:67], v103 offset:20544
	ds_read_b128 v[68:71], v102 offset:61504
	ds_read_b128 v[72:75], v102 offset:64000
	ds_read_b128 v[76:79], v102 offset:64064
	s_waitcnt lgkmcnt(4)
	v_mfma_f32_16x16x32_bf16 v[40:43], v[44:47], v[48:51], v[40:43]
	s_waitcnt lgkmcnt(1)
	v_mfma_f32_16x16x32_bf16 v[24:27], v[44:47], v[72:75], v[24:27]
	ds_read_b128 v[44:47], v103 offset:23040
	ds_read_b128 v[80:83], v103 offset:23104
	s_waitcnt lgkmcnt(1)
	v_mfma_f32_16x16x32_bf16 v[32:35], v[44:47], v[48:51], v[32:35]
	v_mfma_f32_16x16x32_bf16 v[44:47], v[44:47], v[72:75], v[52:55]
	s_nop 2
	ds_read_b128 v[52:55], v103 offset:25600
	ds_read_b128 v[84:87], v103 offset:25664
	s_waitcnt lgkmcnt(1)
	v_mfma_f32_16x16x32_bf16 v[56:59], v[52:55], v[48:51], v[56:59]
	v_mfma_f32_16x16x32_bf16 v[52:55], v[52:55], v[72:75], v[60:63]
	s_nop 2
	ds_read_b128 v[60:63], v103 offset:28160
	ds_read_b128 v[88:91], v103 offset:28224
	s_waitcnt lgkmcnt(1)
	v_mfma_f32_16x16x32_bf16 v[28:31], v[60:63], v[48:51], v[28:31]
	v_mfma_f32_16x16x32_bf16 v[36:39], v[60:63], v[72:75], v[36:39]
	v_mfma_f32_16x16x32_bf16 v[40:43], v[64:67], v[68:71], v[40:43]
	v_mfma_f32_16x16x32_bf16 v[24:27], v[64:67], v[76:79], v[24:27]
	v_mfma_f32_16x16x32_bf16 v[32:35], v[80:83], v[68:71], v[32:35]
	v_mfma_f32_16x16x32_bf16 v[44:47], v[80:83], v[76:79], v[44:47]
	v_mfma_f32_16x16x32_bf16 v[48:51], v[84:87], v[68:71], v[56:59]
	v_mfma_f32_16x16x32_bf16 v[52:55], v[84:87], v[76:79], v[52:55]
	s_waitcnt lgkmcnt(0)
	v_mfma_f32_16x16x32_bf16 v[28:31], v[88:91], v[68:71], v[28:31]
	v_mfma_f32_16x16x32_bf16 v[36:39], v[88:91], v[76:79], v[36:39]
	s_waitcnt vmcnt(4)
	v_lshl_add_u64 v[4:5], v[92:93], 0, s[20:21]
	v_lshl_add_u64 v[92:93], v[92:93], 0, s[24:25]
	v_lshl_add_u64 v[96:97], v[94:95], 0, s[22:23]
	ds_write_b128 v2, v[168:171]
	ds_write_b128 v2, v[172:175] offset:10240
	ds_write_b128 v2, v[176:179] offset:40960
	ds_write_b128 v2, v[180:183] offset:51200
	s_waitcnt lgkmcnt(0)
	s_barrier
	v_lshl_add_u64 v[94:95], v[94:95], 0, s[26:27]
	ds_read_b128 v[56:59], v103
	ds_read_b128 v[60:63], v102 offset:40960
	ds_read_b128 v[64:67], v103 offset:64
	ds_read_b128 v[68:71], v102 offset:41024
	ds_read_b128 v[72:75], v102 offset:43520
	ds_read_b128 v[76:79], v102 offset:43584
	s_waitcnt lgkmcnt(4)
	v_mfma_f32_16x16x32_bf16 v[40:43], v[56:59], v[60:63], v[40:43]
	s_waitcnt lgkmcnt(1)
	v_mfma_f32_16x16x32_bf16 v[24:27], v[56:59], v[72:75], v[24:27]
	ds_read_b128 v[56:59], v103 offset:2560
	ds_read_b128 v[80:83], v103 offset:2624
	s_waitcnt lgkmcnt(1)
	v_mfma_f32_16x16x32_bf16 v[32:35], v[56:59], v[60:63], v[32:35]
	v_mfma_f32_16x16x32_bf16 v[44:47], v[56:59], v[72:75], v[44:47]
	ds_read_b128 v[56:59], v103 offset:5120
	ds_read_b128 v[84:87], v103 offset:5184
	s_waitcnt lgkmcnt(1)
	v_mfma_f32_16x16x32_bf16 v[48:51], v[56:59], v[60:63], v[48:51]
	v_mfma_f32_16x16x32_bf16 v[52:55], v[56:59], v[72:75], v[52:55]
	ds_read_b128 v[56:59], v103 offset:7680
	ds_read_b128 v[88:91], v103 offset:7744
	s_waitcnt lgkmcnt(1)
	v_mfma_f32_16x16x32_bf16 v[28:31], v[56:59], v[60:63], v[28:31]
	v_mfma_f32_16x16x32_bf16 v[36:39], v[56:59], v[72:75], v[36:39]
	v_mfma_f32_16x16x32_bf16 v[40:43], v[64:67], v[68:71], v[40:43]
	v_mfma_f32_16x16x32_bf16 v[24:27], v[64:67], v[76:79], v[24:27]
	v_mfma_f32_16x16x32_bf16 v[32:35], v[80:83], v[68:71], v[32:35]
	v_mfma_f32_16x16x32_bf16 v[44:47], v[80:83], v[76:79], v[44:47]
	v_mfma_f32_16x16x32_bf16 v[48:51], v[84:87], v[68:71], v[48:51]
	v_mfma_f32_16x16x32_bf16 v[52:55], v[84:87], v[76:79], v[52:55]
	s_waitcnt lgkmcnt(0)
	v_mfma_f32_16x16x32_bf16 v[28:31], v[88:91], v[68:71], v[28:31]
	v_mfma_f32_16x16x32_bf16 v[36:39], v[88:91], v[76:79], v[36:39]
	s_waitcnt vmcnt(0)
	ds_write_b128 v2, v[184:187] offset:20480
	ds_write_b128 v2, v[188:191] offset:30720
	ds_write_b128 v2, v[192:195] offset:61440
	ds_write_b128 v101, v[196:199] offset:30720
	s_waitcnt lgkmcnt(0)
	s_barrier
	ds_read_b128 v[56:59], v103 offset:20480
	ds_read_b128 v[60:63], v102 offset:61440
	ds_read_b128 v[64:67], v103 offset:20544
	ds_read_b128 v[68:71], v102 offset:61504
	ds_read_b128 v[72:75], v102 offset:64000
	ds_read_b128 v[76:79], v102 offset:64064
	s_waitcnt lgkmcnt(4)
	v_mfma_f32_16x16x32_bf16 v[40:43], v[56:59], v[60:63], v[40:43]
	s_waitcnt lgkmcnt(1)
	v_mfma_f32_16x16x32_bf16 v[24:27], v[56:59], v[72:75], v[24:27]
	ds_read_b128 v[56:59], v103 offset:23040
	ds_read_b128 v[80:83], v103 offset:23104
	s_waitcnt lgkmcnt(1)
	v_mfma_f32_16x16x32_bf16 v[32:35], v[56:59], v[60:63], v[32:35]
	v_mfma_f32_16x16x32_bf16 v[44:47], v[56:59], v[72:75], v[44:47]
	ds_read_b128 v[56:59], v103 offset:25600
	ds_read_b128 v[84:87], v103 offset:25664
	s_waitcnt lgkmcnt(1)
	v_mfma_f32_16x16x32_bf16 v[48:51], v[56:59], v[60:63], v[48:51]
	v_mfma_f32_16x16x32_bf16 v[52:55], v[56:59], v[72:75], v[52:55]
	ds_read_b128 v[56:59], v103 offset:28160
	ds_read_b128 v[88:91], v103 offset:28224
	s_waitcnt lgkmcnt(1)
	v_mfma_f32_16x16x32_bf16 v[28:31], v[56:59], v[60:63], v[28:31]
	v_mfma_f32_16x16x32_bf16 v[36:39], v[56:59], v[72:75], v[36:39]
	v_mfma_f32_16x16x32_bf16 v[40:43], v[64:67], v[68:71], v[40:43]
	v_mfma_f32_16x16x32_bf16 v[24:27], v[64:67], v[76:79], v[24:27]
	v_mfma_f32_16x16x32_bf16 v[32:35], v[80:83], v[68:71], v[32:35]
	v_mfma_f32_16x16x32_bf16 v[44:47], v[80:83], v[76:79], v[44:47]
	v_mfma_f32_16x16x32_bf16 v[48:51], v[84:87], v[68:71], v[48:51]
	v_mfma_f32_16x16x32_bf16 v[52:55], v[84:87], v[76:79], v[52:55]
	s_waitcnt lgkmcnt(0)
	v_mfma_f32_16x16x32_bf16 v[28:31], v[88:91], v[68:71], v[28:31]
	v_mfma_f32_16x16x32_bf16 v[36:39], v[88:91], v[76:79], v[36:39]
	s_waitcnt vmcnt(0)
	v_lshl_add_u32 v4, v98, 7, 0
	v_lshlrev_b32_e32 v5, 2, v99
	s_lshl_b64 s[30:31], s[28:29], 15
	ds_write_b128 v2, v[8:11]
	ds_write_b128 v2, v[12:15] offset:10240
	ds_write_b128 v2, v[16:19] offset:40960
	ds_write_b128 v2, v[20:23] offset:51200
	v_lshl_or_b32 v2, v100, 2, v7
	v_mul_lo_u32 v2, v2, s38
	v_add3_u32 v2, v4, v5, v2
	v_add_u32_e32 v4, 0x400, v2
	s_waitcnt lgkmcnt(0)
	s_barrier
	ds_write2_b32 v2, v40, v24 offset1:16
	ds_write2_b32 v2, v41, v25 offset0:132 offset1:148
	ds_write2_b32 v4, v42, v26 offset0:8 offset1:24
	ds_write2_b32 v4, v43, v27 offset0:140 offset1:156
	v_add_u32_e32 v4, 0x2000, v2
	ds_write2_b32 v4, v32, v44 offset0:64 offset1:80
	ds_write2_b32 v4, v33, v45 offset0:196 offset1:212
	v_add_u32_e32 v4, 0x2400, v2
	ds_write2_b32 v4, v34, v46 offset0:72 offset1:88
	ds_write2_b32 v4, v35, v47 offset0:204 offset1:220
	v_add_u32_e32 v4, 0x4000, v2
	ds_write2_b32 v4, v48, v52 offset0:128 offset1:144
	v_add_u32_e32 v4, 0x4400, v2
	ds_write2_b32 v4, v49, v53 offset0:4 offset1:20
	ds_write2_b32 v4, v50, v54 offset0:136 offset1:152
	v_add_u32_e32 v4, 0x4800, v2
	ds_write2_b32 v4, v51, v55 offset0:12 offset1:28
	v_add_u32_e32 v4, 0x6000, v2
	ds_write2_b32 v4, v28, v36 offset0:192 offset1:208
	v_add_u32_e32 v4, 0x6400, v2
	ds_write2_b32 v4, v29, v37 offset0:68 offset1:84
	ds_write2_b32 v4, v30, v38 offset0:200 offset1:216
	v_add_u32_e32 v2, 0x6800, v2
	v_mov_b32_e32 v4, v0
	ds_write2_b32 v2, v31, v39 offset0:76 offset1:92
	s_waitcnt lgkmcnt(0)
	s_barrier
	s_add_u32 s30, s0, s30
	v_ashrrev_i32_e32 v7, 4, v4
	v_lshlrev_b32_e32 v2, 3, v4
	v_and_b32_e32 v4, 15, v4
	v_and_b32_e32 v2, 0x78, v2
	v_mul_lo_u32 v5, v7, s38
	v_lshlrev_b32_e32 v4, 5, v4
	s_addc_u32 s31, s1, s31
	v_lshlrev_b32_e32 v8, 7, v7
	v_add3_u32 v9, v5, v4, 0
	v_lshlrev_b32_e32 v4, 2, v2
	s_mov_b32 s29, 0
